# G1 decode tail: 4 K-steps unrolled, 3 K-steps of loads issued up front + double-buffered LDS (one barrier per step)
# speedup vs baseline: 1.0000x; 1.0000x over previous
; template <int MODE>
; PH void gemm_phase(const Params& p, int layer) {
;     ...
;       const int tn = bid & 7, kq = bid >> 3;
;       const int m0 = MP, n0 = tn * 128;
;       const int soff = (tid >> 3) * 72 + (tid & 7) * 8;
;       const u16* gX = X + (size_t)(m0 + (tid >> 3)) * K + (tid & 7) * 8;
;       const u16* gW = W + (size_t)(n0 + (tid >> 3)) * K + (tid & 7) * 8;
;       f32x4 acc[4][4];
; #pragma unroll
;       for (int a = 0; a < 4; ++a)
; #pragma unroll
;         for (int b = 0; b < 4; ++b) acc[a][b] = (f32x4){0.f, 0.f, 0.f, 0.f};
; #pragma unroll 1
;       for (int j = 0; j < 4; ++j) {
;         const int k0 = ((kq * 4 + j + 20) & 31) * 64;
;         u32x4 rx[4], rw[4];
; #pragma unroll
;         for (int i = 0; i < 4; ++i) {
;           rx[i] = *(const u32x4*)(gX + (size_t)i * 32 * K + k0);
;           rw[i] = *(const u32x4*)(gW + (size_t)i * 32 * K + k0);
;         }
;         __syncthreads();
; #pragma unroll
;         for (int i = 0; i < 4; ++i) {
;           *(u32x4*)(sX + soff + i * 32 * 72) = rx[i];
;           *(u32x4*)(sW + soff + i * 32 * 72) = rw[i];
;         }
.LBB0_770:
	v_readlane_b32 s0, v254, 38
	v_readlane_b32 s1, v254, 39
	s_andn2_b64 vcc, exec, s[0:1]
	s_barrier
	s_cbranch_vccnz .LBB0_846
	s_waitcnt vmcnt(6)
	v_ashrrev_i32_e32 v0, 3, v168
	v_lshlrev_b32_e32 v1, 3, v168
	v_and_b32_e32 v2, 56, v1
	v_ashrrev_i32_e32 v1, 31, v0
	v_readlane_b32 s0, v254, 40
	s_waitcnt vmcnt(4)
	v_lshlrev_b64 v[4:5], 12, v[0:1]
	v_lshl_add_u64 v[4:5], s[28:29], 0, v[4:5]
	v_add_u32_e32 v6, s0, v0
	s_movk_i32 s0, 0x48
	v_ashrrev_i32_e32 v7, 31, v6
	v_mad_u64_u32 v[0:1], s[0:1], v0, s0, v[2:3]
	v_lshlrev_b32_e32 v160, 1, v2
	v_lshlrev_b32_e32 v68, 6, v171
	v_lshlrev_b64 v[6:7], 12, v[6:7]
	v_lshl_add_u64 v[2:3], v[4:5], 0, v[160:161]
	s_mov_b64 s[0:1], 0x4000000
	v_lshl_add_u32 v69, v0, 1, 32
	v_or_b32_e32 v0, v68, v169
	v_and_b32_e32 v1, 48, v168
	v_lshl_or_b32 v74, v170, 6, v169
	v_lshl_add_u64 v[6:7], s[40:41], 0, v[6:7]
	v_lshl_add_u64 v[64:65], v[2:3], 0, s[0:1]
	v_add_u32_e32 v1, 32, v1
	v_mul_lo_u32 v2, v0, s11
	v_mul_u32_u24_e32 v3, 0x90, v74
	v_mov_b32_e32 v0, 0
	v_lshl_add_u64 v[66:67], v[6:7], 0, v[160:161]
	s_mov_b32 s0, 0
	v_add_u32_e32 v70, v1, v2
	v_add_u32_e32 v71, v1, v3
	v_mov_b32_e32 v1, v0
	v_mov_b32_e32 v2, v0
	v_mov_b32_e32 v3, v0
	s_waitcnt vmcnt(1)
	v_mov_b32_e32 v16, v0
	v_mov_b32_e32 v17, v0
	v_mov_b32_e32 v18, v0
	v_mov_b32_e32 v19, v0
	v_mov_b32_e32 v32, v0
	v_mov_b32_e32 v33, v0
	v_mov_b32_e32 v34, v0
	v_mov_b32_e32 v35, v0
	v_mov_b32_e32 v48, v0
	v_mov_b32_e32 v49, v0
	v_mov_b32_e32 v50, v0
	v_mov_b32_e32 v51, v0
	v_mov_b32_e32 v4, v0
	v_mov_b32_e32 v5, v0
	v_mov_b32_e32 v6, v0
	v_mov_b32_e32 v7, v0
	v_mov_b32_e32 v20, v0
	v_mov_b32_e32 v21, v0
	v_mov_b32_e32 v22, v0
	v_mov_b32_e32 v23, v0
	s_waitcnt vmcnt(0)
	v_mov_b32_e32 v36, v0
	v_mov_b32_e32 v37, v0
	v_mov_b32_e32 v38, v0
	v_mov_b32_e32 v39, v0
	v_mov_b32_e32 v52, v0
	v_mov_b32_e32 v53, v0
	v_mov_b32_e32 v54, v0
	v_mov_b32_e32 v55, v0
	v_mov_b32_e32 v8, v0
	v_mov_b32_e32 v9, v0
	v_mov_b32_e32 v10, v0
	v_mov_b32_e32 v11, v0
	v_mov_b32_e32 v24, v0
	v_mov_b32_e32 v25, v0
	v_mov_b32_e32 v26, v0
	v_mov_b32_e32 v27, v0
	v_mov_b32_e32 v40, v0
	v_mov_b32_e32 v41, v0
	v_mov_b32_e32 v42, v0
	v_mov_b32_e32 v43, v0
	v_mov_b32_e32 v56, v0
	v_mov_b32_e32 v57, v0
	v_mov_b32_e32 v58, v0
	v_mov_b32_e32 v59, v0
	v_mov_b32_e32 v12, v0
	v_mov_b32_e32 v13, v0
	v_mov_b32_e32 v14, v0
	v_mov_b32_e32 v15, v0
	v_mov_b32_e32 v28, v0
	v_mov_b32_e32 v29, v0
	v_mov_b32_e32 v30, v0
	v_mov_b32_e32 v31, v0
	v_mov_b32_e32 v44, v0
	v_mov_b32_e32 v45, v0
	v_mov_b32_e32 v46, v0
	v_mov_b32_e32 v47, v0
	v_mov_b32_e32 v60, v0
	v_mov_b32_e32 v61, v0
	v_mov_b32_e32 v62, v0
	v_mov_b32_e32 v63, v0
	s_mov_b32 s99, 0
	v_add_u32_e32 v75, 0x4800, v69
	s_add_i32 s1, s65, 0x0
	s_and_b32 s1, s1, 0x7c0
	s_lshl_b32 s2, s1, 1
	v_lshl_add_u64 v[72:73], v[64:65], 0, s[2:3]
	global_load_dwordx4 v[108:111], v[72:73], off
	v_lshl_add_u64 v[72:73], v[66:67], 0, s[2:3]
	global_load_dwordx4 v[112:115], v[72:73], off
	s_add_u32 s98, s2, s66
	v_lshl_add_u64 v[72:73], v[64:65], 0, s[98:99]
	global_load_dwordx4 v[116:119], v[72:73], off
	v_lshl_add_u64 v[72:73], v[66:67], 0, s[98:99]
	global_load_dwordx4 v[120:123], v[72:73], off
	s_add_u32 s98, s2, s67
	v_lshl_add_u64 v[72:73], v[64:65], 0, s[98:99]
	global_load_dwordx4 v[124:127], v[72:73], off
	v_lshl_add_u64 v[72:73], v[66:67], 0, s[98:99]
	global_load_dwordx4 v[128:131], v[72:73], off
	s_add_u32 s98, s2, s68
	v_lshl_add_u64 v[72:73], v[64:65], 0, s[98:99]
	global_load_dwordx4 v[132:135], v[72:73], off
	v_lshl_add_u64 v[72:73], v[66:67], 0, s[98:99]
	global_load_dwordx4 v[136:139], v[72:73], off
	s_add_i32 s1, s65, 0x40
	s_and_b32 s1, s1, 0x7c0
	s_lshl_b32 s2, s1, 1
	v_lshl_add_u64 v[72:73], v[64:65], 0, s[2:3]
	global_load_dwordx4 v[140:143], v[72:73], off
	v_lshl_add_u64 v[72:73], v[66:67], 0, s[2:3]
	global_load_dwordx4 v[144:147], v[72:73], off
	s_add_u32 s98, s2, s66
	v_lshl_add_u64 v[72:73], v[64:65], 0, s[98:99]
	global_load_dwordx4 v[148:151], v[72:73], off
	v_lshl_add_u64 v[72:73], v[66:67], 0, s[98:99]
	global_load_dwordx4 v[152:155], v[72:73], off
	s_add_u32 s98, s2, s67
	v_lshl_add_u64 v[72:73], v[64:65], 0, s[98:99]
	global_load_dwordx4 v[156:159], v[72:73], off
	v_lshl_add_u64 v[72:73], v[66:67], 0, s[98:99]
	global_load_dwordx4 v[204:207], v[72:73], off
	s_add_u32 s98, s2, s68
	v_lshl_add_u64 v[72:73], v[64:65], 0, s[98:99]
	global_load_dwordx4 v[240:243], v[72:73], off
	v_lshl_add_u64 v[72:73], v[66:67], 0, s[98:99]
	global_load_dwordx4 v[244:247], v[72:73], off
	s_add_i32 s1, s65, 0x80
	s_and_b32 s1, s1, 0x7c0
	s_lshl_b32 s2, s1, 1
	v_lshl_add_u64 v[72:73], v[64:65], 0, s[2:3]
	global_load_dwordx4 v[208:211], v[72:73], off
	v_lshl_add_u64 v[72:73], v[66:67], 0, s[2:3]
	global_load_dwordx4 v[212:215], v[72:73], off
	s_add_u32 s98, s2, s66
	v_lshl_add_u64 v[72:73], v[64:65], 0, s[98:99]
	global_load_dwordx4 v[216:219], v[72:73], off
	v_lshl_add_u64 v[72:73], v[66:67], 0, s[98:99]
	global_load_dwordx4 v[220:223], v[72:73], off
	s_add_u32 s98, s2, s67
	v_lshl_add_u64 v[72:73], v[64:65], 0, s[98:99]
	global_load_dwordx4 v[224:227], v[72:73], off
	v_lshl_add_u64 v[72:73], v[66:67], 0, s[98:99]
	global_load_dwordx4 v[228:231], v[72:73], off
	s_add_u32 s98, s2, s68
	v_lshl_add_u64 v[72:73], v[64:65], 0, s[98:99]
	global_load_dwordx4 v[232:235], v[72:73], off
	v_lshl_add_u64 v[72:73], v[66:67], 0, s[98:99]
	global_load_dwordx4 v[248:251], v[72:73], off
	s_waitcnt vmcnt(23)
	ds_write_b128 v69, v[108:111]
	s_waitcnt vmcnt(22)
	ds_write_b128 v69, v[112:115] offset:36864
	s_waitcnt vmcnt(21)
	ds_write_b128 v69, v[116:119] offset:4608
	s_waitcnt vmcnt(20)
	ds_write_b128 v69, v[120:123] offset:41472
	s_waitcnt vmcnt(19)
	ds_write_b128 v69, v[124:127] offset:9216
	s_waitcnt vmcnt(18)
	ds_write_b128 v69, v[128:131] offset:46080
	s_waitcnt vmcnt(17)
	ds_write_b128 v69, v[132:135] offset:13824
	s_waitcnt vmcnt(16)
	ds_write_b128 v69, v[136:139] offset:50688
	s_waitcnt lgkmcnt(0)
	s_add_i32 s1, s65, 0xc0
	s_and_b32 s1, s1, 0x7c0
	s_lshl_b32 s2, s1, 1
	v_lshl_add_u64 v[72:73], v[64:65], 0, s[2:3]
	global_load_dwordx4 v[108:111], v[72:73], off
	v_lshl_add_u64 v[72:73], v[66:67], 0, s[2:3]
	global_load_dwordx4 v[112:115], v[72:73], off
	s_add_u32 s98, s2, s66
	v_lshl_add_u64 v[72:73], v[64:65], 0, s[98:99]
	global_load_dwordx4 v[116:119], v[72:73], off
	v_lshl_add_u64 v[72:73], v[66:67], 0, s[98:99]
	global_load_dwordx4 v[120:123], v[72:73], off
	s_add_u32 s98, s2, s67
	v_lshl_add_u64 v[72:73], v[64:65], 0, s[98:99]
	global_load_dwordx4 v[124:127], v[72:73], off
	v_lshl_add_u64 v[72:73], v[66:67], 0, s[98:99]
	global_load_dwordx4 v[128:131], v[72:73], off
	s_add_u32 s98, s2, s68
	v_lshl_add_u64 v[72:73], v[64:65], 0, s[98:99]
	global_load_dwordx4 v[132:135], v[72:73], off
	v_lshl_add_u64 v[72:73], v[66:67], 0, s[98:99]
	global_load_dwordx4 v[136:139], v[72:73], off
	s_barrier
; DI f32x4 mfma16(bf16x8 a, bf16x8 b, f32x4 c) { return __builtin_amdgcn_mfma_f32_16x16x32_bf16(a, b, c, 0, 0, 0); }
; template <int MODE>
; PH void gemm_phase(const Params& p, int layer) {
;     ...
;         __syncthreads();
; #pragma unroll
;         for (int i = 0; i < 4; ++i) {
;           *(u32x4*)(sX + soff + i * 32 * 72) = rx[i];
;           *(u32x4*)(sW + soff + i * 32 * 72) = rw[i];
;         }
;         __syncthreads();
; #pragma unroll
;         for (int ks = 0; ks < 2; ++ks) {
;           bf16x8 wf[4], xf[4];
; #pragma unroll
;           for (int i = 0; i < 4; ++i) {
;             wf[i] = ldfrag(sW, 72, wn * 64 + i * 16, ks * 32, lane);
;             xf[i] = ldfrag(sX, 72, wm * 64 + i * 16, ks * 32, lane);
;           }
; #pragma unroll
;           for (int nt = 0; nt < 4; ++nt)
; #pragma unroll
;             for (int mt = 0; mt < 4; ++mt) acc[nt][mt] = mfma16(wf[nt], xf[mt], acc[nt][mt]);
;         }
	ds_read_b128 v[76:79], v70 offset:36864
	ds_read_b128 v[80:83], v71
	ds_read_b128 v[84:87], v70 offset:39168
	ds_read_b128 v[88:91], v71 offset:2304
	ds_read_b128 v[92:95], v70 offset:41472
	ds_read_b128 v[96:99], v71 offset:4608
	ds_read_b128 v[100:103], v70 offset:43776
	ds_read_b128 v[104:107], v71 offset:6912
	s_waitcnt lgkmcnt(6)
	v_mfma_f32_16x16x32_bf16 v[60:63], v[76:79], v[80:83], v[60:63]
	s_waitcnt lgkmcnt(4)
	v_mfma_f32_16x16x32_bf16 v[44:47], v[76:79], v[88:91], v[44:47]
	s_waitcnt lgkmcnt(2)
	v_mfma_f32_16x16x32_bf16 v[28:31], v[76:79], v[96:99], v[28:31]
	s_waitcnt lgkmcnt(0)
	v_mfma_f32_16x16x32_bf16 v[12:15], v[76:79], v[104:107], v[12:15]
	v_mfma_f32_16x16x32_bf16 v[56:59], v[84:87], v[80:83], v[56:59]
	v_mfma_f32_16x16x32_bf16 v[40:43], v[84:87], v[88:91], v[40:43]
	v_mfma_f32_16x16x32_bf16 v[24:27], v[84:87], v[96:99], v[24:27]
	v_mfma_f32_16x16x32_bf16 v[8:11], v[84:87], v[104:107], v[8:11]
	v_mfma_f32_16x16x32_bf16 v[52:55], v[92:95], v[80:83], v[52:55]
	v_mfma_f32_16x16x32_bf16 v[36:39], v[92:95], v[88:91], v[36:39]
	v_mfma_f32_16x16x32_bf16 v[20:23], v[92:95], v[96:99], v[20:23]
	v_mfma_f32_16x16x32_bf16 v[4:7], v[92:95], v[104:107], v[4:7]
	v_mfma_f32_16x16x32_bf16 v[48:51], v[100:103], v[80:83], v[48:51]
	v_mfma_f32_16x16x32_bf16 v[32:35], v[100:103], v[88:91], v[32:35]
	v_mfma_f32_16x16x32_bf16 v[16:19], v[100:103], v[96:99], v[16:19]
	v_mfma_f32_16x16x32_bf16 v[0:3], v[100:103], v[104:107], v[0:3]
	ds_read_b128 v[76:79], v70 offset:36928
	ds_read_b128 v[80:83], v71 offset:64
	ds_read_b128 v[84:87], v70 offset:39232
	ds_read_b128 v[88:91], v71 offset:2368
	ds_read_b128 v[92:95], v70 offset:41536
	ds_read_b128 v[96:99], v71 offset:4672
	ds_read_b128 v[100:103], v70 offset:43840
	ds_read_b128 v[104:107], v71 offset:6976
	s_waitcnt lgkmcnt(6)
	v_mfma_f32_16x16x32_bf16 v[60:63], v[76:79], v[80:83], v[60:63]
	s_waitcnt lgkmcnt(4)
	v_mfma_f32_16x16x32_bf16 v[44:47], v[76:79], v[88:91], v[44:47]
	s_waitcnt lgkmcnt(2)
	v_mfma_f32_16x16x32_bf16 v[28:31], v[76:79], v[96:99], v[28:31]
	s_waitcnt lgkmcnt(0)
	v_mfma_f32_16x16x32_bf16 v[12:15], v[76:79], v[104:107], v[12:15]
	v_mfma_f32_16x16x32_bf16 v[56:59], v[84:87], v[80:83], v[56:59]
	v_mfma_f32_16x16x32_bf16 v[40:43], v[84:87], v[88:91], v[40:43]
	v_mfma_f32_16x16x32_bf16 v[24:27], v[84:87], v[96:99], v[24:27]
	v_mfma_f32_16x16x32_bf16 v[8:11], v[84:87], v[104:107], v[8:11]
	v_mfma_f32_16x16x32_bf16 v[52:55], v[92:95], v[80:83], v[52:55]
	v_mfma_f32_16x16x32_bf16 v[36:39], v[92:95], v[88:91], v[36:39]
	v_mfma_f32_16x16x32_bf16 v[20:23], v[92:95], v[96:99], v[20:23]
	v_mfma_f32_16x16x32_bf16 v[4:7], v[92:95], v[104:107], v[4:7]
	v_mfma_f32_16x16x32_bf16 v[48:51], v[100:103], v[80:83], v[48:51]
	v_mfma_f32_16x16x32_bf16 v[32:35], v[100:103], v[88:91], v[32:35]
	v_mfma_f32_16x16x32_bf16 v[16:19], v[100:103], v[96:99], v[16:19]
	v_mfma_f32_16x16x32_bf16 v[0:3], v[100:103], v[104:107], v[0:3]
	s_waitcnt vmcnt(23)
	ds_write_b128 v75, v[140:143]
	s_waitcnt vmcnt(22)
	ds_write_b128 v75, v[144:147] offset:36864
	s_waitcnt vmcnt(21)
	ds_write_b128 v75, v[148:151] offset:4608
	s_waitcnt vmcnt(20)
	ds_write_b128 v75, v[152:155] offset:41472
	s_waitcnt vmcnt(19)
	ds_write_b128 v75, v[156:159] offset:9216
	s_waitcnt vmcnt(18)
	ds_write_b128 v75, v[204:207] offset:46080
	s_waitcnt vmcnt(17)
	ds_write_b128 v75, v[240:243] offset:13824
	s_waitcnt vmcnt(16)
	ds_write_b128 v75, v[244:247] offset:50688
	s_waitcnt lgkmcnt(0)
	s_barrier
	ds_read_b128 v[76:79], v70 offset:55296
	ds_read_b128 v[80:83], v71 offset:18432
	ds_read_b128 v[84:87], v70 offset:57600
	ds_read_b128 v[88:91], v71 offset:20736
	ds_read_b128 v[92:95], v70 offset:59904
	ds_read_b128 v[96:99], v71 offset:23040
	ds_read_b128 v[100:103], v70 offset:62208
	ds_read_b128 v[104:107], v71 offset:25344
	s_waitcnt lgkmcnt(6)
	v_mfma_f32_16x16x32_bf16 v[60:63], v[76:79], v[80:83], v[60:63]
	s_waitcnt lgkmcnt(4)
	v_mfma_f32_16x16x32_bf16 v[44:47], v[76:79], v[88:91], v[44:47]
	s_waitcnt lgkmcnt(2)
	v_mfma_f32_16x16x32_bf16 v[28:31], v[76:79], v[96:99], v[28:31]
	s_waitcnt lgkmcnt(0)
	v_mfma_f32_16x16x32_bf16 v[12:15], v[76:79], v[104:107], v[12:15]
	v_mfma_f32_16x16x32_bf16 v[56:59], v[84:87], v[80:83], v[56:59]
	v_mfma_f32_16x16x32_bf16 v[40:43], v[84:87], v[88:91], v[40:43]
	v_mfma_f32_16x16x32_bf16 v[24:27], v[84:87], v[96:99], v[24:27]
	v_mfma_f32_16x16x32_bf16 v[8:11], v[84:87], v[104:107], v[8:11]
	v_mfma_f32_16x16x32_bf16 v[52:55], v[92:95], v[80:83], v[52:55]
	v_mfma_f32_16x16x32_bf16 v[36:39], v[92:95], v[88:91], v[36:39]
	v_mfma_f32_16x16x32_bf16 v[20:23], v[92:95], v[96:99], v[20:23]
	v_mfma_f32_16x16x32_bf16 v[4:7], v[92:95], v[104:107], v[4:7]
	v_mfma_f32_16x16x32_bf16 v[48:51], v[100:103], v[80:83], v[48:51]
	v_mfma_f32_16x16x32_bf16 v[32:35], v[100:103], v[88:91], v[32:35]
	v_mfma_f32_16x16x32_bf16 v[16:19], v[100:103], v[96:99], v[16:19]
	v_mfma_f32_16x16x32_bf16 v[0:3], v[100:103], v[104:107], v[0:3]
	ds_read_b128 v[76:79], v70 offset:55360
	ds_read_b128 v[80:83], v71 offset:18496
	ds_read_b128 v[84:87], v70 offset:57664
	ds_read_b128 v[88:91], v71 offset:20800
	ds_read_b128 v[92:95], v70 offset:59968
	ds_read_b128 v[96:99], v71 offset:23104
	ds_read_b128 v[100:103], v70 offset:62272
	ds_read_b128 v[104:107], v71 offset:25408
	s_waitcnt lgkmcnt(6)
	v_mfma_f32_16x16x32_bf16 v[60:63], v[76:79], v[80:83], v[60:63]
	s_waitcnt lgkmcnt(4)
	v_mfma_f32_16x16x32_bf16 v[44:47], v[76:79], v[88:91], v[44:47]
	s_waitcnt lgkmcnt(2)
	v_mfma_f32_16x16x32_bf16 v[28:31], v[76:79], v[96:99], v[28:31]
	s_waitcnt lgkmcnt(0)
	v_mfma_f32_16x16x32_bf16 v[12:15], v[76:79], v[104:107], v[12:15]
	v_mfma_f32_16x16x32_bf16 v[56:59], v[84:87], v[80:83], v[56:59]
	v_mfma_f32_16x16x32_bf16 v[40:43], v[84:87], v[88:91], v[40:43]
	v_mfma_f32_16x16x32_bf16 v[24:27], v[84:87], v[96:99], v[24:27]
	v_mfma_f32_16x16x32_bf16 v[8:11], v[84:87], v[104:107], v[8:11]
	v_mfma_f32_16x16x32_bf16 v[52:55], v[92:95], v[80:83], v[52:55]
	v_mfma_f32_16x16x32_bf16 v[36:39], v[92:95], v[88:91], v[36:39]
	v_mfma_f32_16x16x32_bf16 v[20:23], v[92:95], v[96:99], v[20:23]
	v_mfma_f32_16x16x32_bf16 v[4:7], v[92:95], v[104:107], v[4:7]
	v_mfma_f32_16x16x32_bf16 v[48:51], v[100:103], v[80:83], v[48:51]
	v_mfma_f32_16x16x32_bf16 v[32:35], v[100:103], v[88:91], v[32:35]
	v_mfma_f32_16x16x32_bf16 v[16:19], v[100:103], v[96:99], v[16:19]
	v_mfma_f32_16x16x32_bf16 v[0:3], v[100:103], v[104:107], v[0:3]
	s_waitcnt vmcnt(15)
	ds_write_b128 v69, v[208:211]
	s_waitcnt vmcnt(14)
	ds_write_b128 v69, v[212:215] offset:36864
	s_waitcnt vmcnt(13)
	ds_write_b128 v69, v[216:219] offset:4608
	s_waitcnt vmcnt(12)
	ds_write_b128 v69, v[220:223] offset:41472
	s_waitcnt vmcnt(11)
	ds_write_b128 v69, v[224:227] offset:9216
	s_waitcnt vmcnt(10)
	ds_write_b128 v69, v[228:231] offset:46080
	s_waitcnt vmcnt(9)
	ds_write_b128 v69, v[232:235] offset:13824
	s_waitcnt vmcnt(8)
	ds_write_b128 v69, v[248:251] offset:50688
	s_waitcnt lgkmcnt(0)
	s_barrier
; DI f32x4 mfma16(bf16x8 a, bf16x8 b, f32x4 c) { return __builtin_amdgcn_mfma_f32_16x16x32_bf16(a, b, c, 0, 0, 0); }
; template <int MODE>
; PH void gemm_phase(const Params& p, int layer) {
;     ...
;         for (int i = 0; i < 4; ++i) {
;           *(u32x4*)(sX + soff + i * 32 * 72) = rx[i];
;           *(u32x4*)(sW + soff + i * 32 * 72) = rw[i];
;         }
;         __syncthreads();
; #pragma unroll
;         for (int ks = 0; ks < 2; ++ks) {
;           bf16x8 wf[4], xf[4];
; #pragma unroll
;           for (int i = 0; i < 4; ++i) {
;             wf[i] = ldfrag(sW, 72, wn * 64 + i * 16, ks * 32, lane);
;             xf[i] = ldfrag(sX, 72, wm * 64 + i * 16, ks * 32, lane);
;           }
; #pragma unroll
;           for (int nt = 0; nt < 4; ++nt)
; #pragma unroll
;             for (int mt = 0; mt < 4; ++mt) acc[nt][mt] = mfma16(wf[nt], xf[mt], acc[nt][mt]);
;         }
	ds_read_b128 v[76:79], v70 offset:36864
	ds_read_b128 v[80:83], v71
	ds_read_b128 v[84:87], v70 offset:39168
	ds_read_b128 v[88:91], v71 offset:2304
	ds_read_b128 v[92:95], v70 offset:41472
	ds_read_b128 v[96:99], v71 offset:4608
	ds_read_b128 v[100:103], v70 offset:43776
	ds_read_b128 v[104:107], v71 offset:6912
	s_waitcnt lgkmcnt(6)
	v_mfma_f32_16x16x32_bf16 v[60:63], v[76:79], v[80:83], v[60:63]
	s_waitcnt lgkmcnt(4)
	v_mfma_f32_16x16x32_bf16 v[44:47], v[76:79], v[88:91], v[44:47]
	s_waitcnt lgkmcnt(2)
	v_mfma_f32_16x16x32_bf16 v[28:31], v[76:79], v[96:99], v[28:31]
	s_waitcnt lgkmcnt(0)
	v_mfma_f32_16x16x32_bf16 v[12:15], v[76:79], v[104:107], v[12:15]
	v_mfma_f32_16x16x32_bf16 v[56:59], v[84:87], v[80:83], v[56:59]
	v_mfma_f32_16x16x32_bf16 v[40:43], v[84:87], v[88:91], v[40:43]
	v_mfma_f32_16x16x32_bf16 v[24:27], v[84:87], v[96:99], v[24:27]
	v_mfma_f32_16x16x32_bf16 v[8:11], v[84:87], v[104:107], v[8:11]
	v_mfma_f32_16x16x32_bf16 v[52:55], v[92:95], v[80:83], v[52:55]
	v_mfma_f32_16x16x32_bf16 v[36:39], v[92:95], v[88:91], v[36:39]
	v_mfma_f32_16x16x32_bf16 v[20:23], v[92:95], v[96:99], v[20:23]
	v_mfma_f32_16x16x32_bf16 v[4:7], v[92:95], v[104:107], v[4:7]
	v_mfma_f32_16x16x32_bf16 v[48:51], v[100:103], v[80:83], v[48:51]
	v_mfma_f32_16x16x32_bf16 v[32:35], v[100:103], v[88:91], v[32:35]
	v_mfma_f32_16x16x32_bf16 v[16:19], v[100:103], v[96:99], v[16:19]
	v_mfma_f32_16x16x32_bf16 v[0:3], v[100:103], v[104:107], v[0:3]
	ds_read_b128 v[76:79], v70 offset:36928
	ds_read_b128 v[80:83], v71 offset:64
	ds_read_b128 v[84:87], v70 offset:39232
	ds_read_b128 v[88:91], v71 offset:2368
	ds_read_b128 v[92:95], v70 offset:41536
	ds_read_b128 v[96:99], v71 offset:4672
	ds_read_b128 v[100:103], v70 offset:43840
	ds_read_b128 v[104:107], v71 offset:6976
	s_waitcnt lgkmcnt(6)
	v_mfma_f32_16x16x32_bf16 v[60:63], v[76:79], v[80:83], v[60:63]
	s_waitcnt lgkmcnt(4)
	v_mfma_f32_16x16x32_bf16 v[44:47], v[76:79], v[88:91], v[44:47]
	s_waitcnt lgkmcnt(2)
	v_mfma_f32_16x16x32_bf16 v[28:31], v[76:79], v[96:99], v[28:31]
	s_waitcnt lgkmcnt(0)
	v_mfma_f32_16x16x32_bf16 v[12:15], v[76:79], v[104:107], v[12:15]
	v_mfma_f32_16x16x32_bf16 v[56:59], v[84:87], v[80:83], v[56:59]
	v_mfma_f32_16x16x32_bf16 v[40:43], v[84:87], v[88:91], v[40:43]
	v_mfma_f32_16x16x32_bf16 v[24:27], v[84:87], v[96:99], v[24:27]
	v_mfma_f32_16x16x32_bf16 v[8:11], v[84:87], v[104:107], v[8:11]
	v_mfma_f32_16x16x32_bf16 v[52:55], v[92:95], v[80:83], v[52:55]
	v_mfma_f32_16x16x32_bf16 v[36:39], v[92:95], v[88:91], v[36:39]
	v_mfma_f32_16x16x32_bf16 v[20:23], v[92:95], v[96:99], v[20:23]
	v_mfma_f32_16x16x32_bf16 v[4:7], v[92:95], v[104:107], v[4:7]
	v_mfma_f32_16x16x32_bf16 v[48:51], v[100:103], v[80:83], v[48:51]
	v_mfma_f32_16x16x32_bf16 v[32:35], v[100:103], v[88:91], v[32:35]
	v_mfma_f32_16x16x32_bf16 v[16:19], v[100:103], v[96:99], v[16:19]
	v_mfma_f32_16x16x32_bf16 v[0:3], v[100:103], v[104:107], v[0:3]
	s_waitcnt vmcnt(7)
	ds_write_b128 v75, v[108:111]
	s_waitcnt vmcnt(6)
	ds_write_b128 v75, v[112:115] offset:36864
	s_waitcnt vmcnt(5)
	ds_write_b128 v75, v[116:119] offset:4608
	s_waitcnt vmcnt(4)
	ds_write_b128 v75, v[120:123] offset:41472
	s_waitcnt vmcnt(3)
	ds_write_b128 v75, v[124:127] offset:9216
	s_waitcnt vmcnt(2)
	ds_write_b128 v75, v[128:131] offset:46080
	s_waitcnt vmcnt(1)
	ds_write_b128 v75, v[132:135] offset:13824
	s_waitcnt vmcnt(0)
	ds_write_b128 v75, v[136:139] offset:50688
	s_waitcnt lgkmcnt(0)
	s_barrier
; template <int MODE>
; PH void gemm_phase(const Params& p, int layer) {
;     ...
;       float* PRE = (float*)(p.ws + WS_PRE);
;       const float* SSQ = (const float*)(p.ws + WS_SSQ);
;       const float alpha = 1.681792830507429f;
; #pragma unroll
;       for (int mt = 0; mt < 4; ++mt) {
;         const int m = m0 + wm * 64 + mt * 16 + l15;
;         float rs = 1.f;
;         if (kq < 3) {
;           const float4 s0 = *(const float4*)(SSQ + (size_t)m * 12), s1 = *(const float4*)(SSQ + (size_t)m * 12 + 4), s2 = *(const float4*)(SSQ + (size_t)m * 12 + 8);
;           const float ss = s0.x + s0.y + s0.z + s0.w + s1.x + s1.y + s1.z + s1.w + s2.x + s2.y + s2.z + s2.w;
;           rs = rsqrtf(ss * (1.f / 768.f) + 1e-5f);
;         }
	ds_read_b128 v[76:79], v70 offset:55296
	ds_read_b128 v[80:83], v71 offset:18432
	ds_read_b128 v[84:87], v70 offset:57600
	ds_read_b128 v[88:91], v71 offset:20736
	ds_read_b128 v[92:95], v70 offset:59904
	ds_read_b128 v[96:99], v71 offset:23040
	ds_read_b128 v[100:103], v70 offset:62208
	ds_read_b128 v[104:107], v71 offset:25344
	s_waitcnt lgkmcnt(6)
	v_mfma_f32_16x16x32_bf16 v[60:63], v[76:79], v[80:83], v[60:63]
	s_waitcnt lgkmcnt(4)
	v_mfma_f32_16x16x32_bf16 v[44:47], v[76:79], v[88:91], v[44:47]
	s_waitcnt lgkmcnt(2)
	v_mfma_f32_16x16x32_bf16 v[28:31], v[76:79], v[96:99], v[28:31]
	s_waitcnt lgkmcnt(0)
	v_mfma_f32_16x16x32_bf16 v[12:15], v[76:79], v[104:107], v[12:15]
	v_mfma_f32_16x16x32_bf16 v[56:59], v[84:87], v[80:83], v[56:59]
	v_mfma_f32_16x16x32_bf16 v[40:43], v[84:87], v[88:91], v[40:43]
	v_mfma_f32_16x16x32_bf16 v[24:27], v[84:87], v[96:99], v[24:27]
	v_mfma_f32_16x16x32_bf16 v[8:11], v[84:87], v[104:107], v[8:11]
	v_mfma_f32_16x16x32_bf16 v[52:55], v[92:95], v[80:83], v[52:55]
	v_mfma_f32_16x16x32_bf16 v[36:39], v[92:95], v[88:91], v[36:39]
	v_mfma_f32_16x16x32_bf16 v[20:23], v[92:95], v[96:99], v[20:23]
	v_mfma_f32_16x16x32_bf16 v[4:7], v[92:95], v[104:107], v[4:7]
	v_mfma_f32_16x16x32_bf16 v[48:51], v[100:103], v[80:83], v[48:51]
	v_mfma_f32_16x16x32_bf16 v[32:35], v[100:103], v[88:91], v[32:35]
	v_mfma_f32_16x16x32_bf16 v[16:19], v[100:103], v[96:99], v[16:19]
	v_mfma_f32_16x16x32_bf16 v[0:3], v[100:103], v[104:107], v[0:3]
	ds_read_b128 v[76:79], v70 offset:55360
	ds_read_b128 v[80:83], v71 offset:18496
	ds_read_b128 v[84:87], v70 offset:57664
	ds_read_b128 v[88:91], v71 offset:20800
	ds_read_b128 v[92:95], v70 offset:59968
	ds_read_b128 v[96:99], v71 offset:23104
	ds_read_b128 v[100:103], v70 offset:62272
	ds_read_b128 v[104:107], v71 offset:25408
	s_waitcnt lgkmcnt(6)
	v_mfma_f32_16x16x32_bf16 v[60:63], v[76:79], v[80:83], v[60:63]
	s_waitcnt lgkmcnt(4)
	v_mfma_f32_16x16x32_bf16 v[44:47], v[76:79], v[88:91], v[44:47]
	s_waitcnt lgkmcnt(2)
	v_mfma_f32_16x16x32_bf16 v[28:31], v[76:79], v[96:99], v[28:31]
	s_waitcnt lgkmcnt(0)
	v_mfma_f32_16x16x32_bf16 v[12:15], v[76:79], v[104:107], v[12:15]
	v_mfma_f32_16x16x32_bf16 v[56:59], v[84:87], v[80:83], v[56:59]
	v_mfma_f32_16x16x32_bf16 v[40:43], v[84:87], v[88:91], v[40:43]
	v_mfma_f32_16x16x32_bf16 v[24:27], v[84:87], v[96:99], v[24:27]
	v_mfma_f32_16x16x32_bf16 v[8:11], v[84:87], v[104:107], v[8:11]
	v_mfma_f32_16x16x32_bf16 v[52:55], v[92:95], v[80:83], v[52:55]
	v_mfma_f32_16x16x32_bf16 v[36:39], v[92:95], v[88:91], v[36:39]
	v_mfma_f32_16x16x32_bf16 v[20:23], v[92:95], v[96:99], v[20:23]
	v_mfma_f32_16x16x32_bf16 v[4:7], v[92:95], v[104:107], v[4:7]
	v_mfma_f32_16x16x32_bf16 v[48:51], v[100:103], v[80:83], v[48:51]
	v_mfma_f32_16x16x32_bf16 v[32:35], v[100:103], v[88:91], v[32:35]
	v_mfma_f32_16x16x32_bf16 v[16:19], v[100:103], v[96:99], v[16:19]
	v_mfma_f32_16x16x32_bf16 v[0:3], v[100:103], v[104:107], v[0:3]
	s_movk_i32 s0, 0x100
	s_nop 0
	s_nop 0
	s_nop 0
	s_nop 0
	s_nop 0
	s_nop 0
	s_nop 0
	s_nop 0
	s_nop 0
	s_nop 0
	s_nop 0
	s_nop 0
	s_nop 0
	s_nop 0
	s_nop 0
	s_nop 0
	v_readlane_b32 s0, v254, 41
	v_readlane_b32 s1, v254, 42
	v_or_b32_e32 v64, 0x4000, v74
	v_mov_b32_e32 v75, 1.0
	s_and_b64 vcc, exec, s[0:1]
	s_cbranch_vccz .LBB0_775
	v_mul_u32_u24_e32 v65, 12, v64
	v_readlane_b32 s0, v254, 22
	v_lshlrev_b32_e32 v65, 2, v65
	v_readlane_b32 s1, v254, 23
	s_nop 4
	global_load_dwordx4 v[70:73], v65, s[0:1]
	global_load_dwordx4 v[76:79], v65, s[0:1] offset:16
	global_load_dwordx4 v[80:83], v65, s[0:1] offset:32
	s_mov_b32 s0, 0x800000
	s_waitcnt vmcnt(2)
	v_add_f32_e32 v65, v70, v71
	v_add_f32_e32 v65, v65, v72
	v_add_f32_e32 v65, v65, v73
	s_waitcnt vmcnt(1)
	v_add_f32_e32 v65, v65, v76
	v_add_f32_e32 v65, v65, v77
	v_add_f32_e32 v65, v65, v78
	v_add_f32_e32 v65, v65, v79
	s_waitcnt vmcnt(0)
	v_add_f32_e32 v65, v65, v80
	v_add_f32_e32 v65, v65, v81
	v_add_f32_e32 v65, v65, v82
	v_add_f32_e32 v65, v65, v83
	v_fmamk_f32 v65, v65, 0x3aaaaaab, v186
	v_mul_f32_e32 v66, 0x4b800000, v65
	v_cmp_gt_f32_e32 vcc, s0, v65
	s_nop 1
	v_cndmask_b32_e32 v65, v65, v66, vcc
	v_rsq_f32_e32 v65, v65
	s_nop 0
	v_mul_f32_e32 v66, 0x45800000, v65
	v_cndmask_b32_e32 v75, v65, v66, vcc
